# speedup vs baseline: 1.0056x; 1.0056x over previous
; __device__ __forceinline__ float siluf_(float x) { return x / (1.f + __expf(-x)); }
; __device__ __forceinline__ void prep_compute(const PrepRegs& R, const PrepW& W, KP P, int l, int r, int b, int t, int tid, u16* PROJ, u16* XBC, float* DT, u16* ASC, bool dry) {
;     ...
;       if (tid < 384) {
;         const int c0 = tid * 8;
;         float acc[8], raw[8];
; #pragma unroll
;         for (int i = 0; i < 8; ++i) acc[i] = W.cb[i];
; #pragma unroll
;         for (int j = 0; j < 4; ++j) {
;           unpack8(c4[j], raw);
;           const float* w = W.cw[j];
; #pragma unroll
;           for (int i = 0; i < 8; ++i) acc[i] += w[i] * raw[i];
;         }
;         float o[8];
; #pragma unroll
;         for (int i = 0; i < 8; ++i) o[i] = siluf_(acc[i]);
;         *(uint4*)(XBC + (long)r * 3072 + c0) = pack8(o);
.LBB0_368:
	s_waitcnt vmcnt(2)
	v_lshlrev_b32_e32 v83, 16, v29
	v_lshlrev_b32_e32 v82, 16, v28
	v_and_b32_e32 v87, 0xffff0000, v29
	v_and_b32_e32 v86, 0xffff0000, v28
	v_lshlrev_b32_e32 v196, 16, v36
	v_and_b32_e32 v206, 0xffff0000, v36
	v_lshlrev_b32_e32 v197, 16, v37
	v_and_b32_e32 v207, 0xffff0000, v37
	v_pk_fma_f32 v[82:83], v[96:97], v[82:83], v[94:95]
	v_pk_fma_f32 v[86:87], v[114:115], v[86:87], v[112:113]
	v_pk_fma_f32 v[82:83], v[100:101], v[196:197], v[82:83]
	v_pk_fma_f32 v[86:87], v[116:117], v[206:207], v[86:87]
	v_lshlrev_b32_e32 v197, 16, v41
	v_lshlrev_b32_e32 v196, 16, v40
	v_and_b32_e32 v207, 0xffff0000, v41
	v_and_b32_e32 v206, 0xffff0000, v40
	v_pk_fma_f32 v[208:209], v[102:103], v[196:197], v[82:83]
	v_pk_fma_f32 v[86:87], v[120:121], v[206:207], v[86:87]
	s_waitcnt vmcnt(1)
	v_and_b32_e32 v83, 0xffff0000, v45
	v_and_b32_e32 v82, 0xffff0000, v44
	v_lshlrev_b32_e32 v197, 16, v45
	v_lshlrev_b32_e32 v196, 16, v44
	v_pk_fma_f32 v[86:87], v[122:123], v[82:83], v[86:87]
	v_pk_fma_f32 v[206:207], v[98:99], v[196:197], v[208:209]
	v_mul_f32_e32 v209, 0xbfb8aa3b, v86
	v_mul_f32_e32 v208, 0xbfb8aa3b, v206
	v_exp_f32_e32 v210, v209
	v_mul_f32_e32 v209, 0xbfb8aa3b, v207
	v_exp_f32_e32 v208, v208
	v_exp_f32_e32 v209, v209
	v_lshlrev_b32_e32 v85, 16, v31
	v_lshlrev_b32_e32 v84, 16, v30
	v_and_b32_e32 v89, 0xffff0000, v31
	v_pk_add_f32 v[208:209], v[208:209], 1.0 op_sel_hi:[1,0]
	v_and_b32_e32 v88, 0xffff0000, v30
	v_div_scale_f32 v211, s[0:1], v208, v208, v206
	v_rcp_f32_e32 v212, v211
	v_lshlrev_b32_e32 v200, 16, v38
	v_and_b32_e32 v198, 0xffff0000, v38
	v_lshlrev_b32_e32 v201, 16, v39
	v_fma_f32 v213, -v211, v212, 1.0
	v_fmac_f32_e32 v212, v213, v212
	v_div_scale_f32 v213, vcc, v206, v208, v206
	v_mul_f32_e32 v214, v213, v212
	v_fma_f32 v215, -v211, v214, v213
	v_fmac_f32_e32 v214, v215, v212
	v_fma_f32 v211, -v211, v214, v213
	v_div_fmas_f32 v211, v211, v212, v214
	v_div_fixup_f32 v208, v211, v208, v206
	v_div_scale_f32 v206, s[0:1], v209, v209, v207
	v_rcp_f32_e32 v211, v206
	v_and_b32_e32 v199, 0xffff0000, v39
	v_pk_fma_f32 v[84:85], v[132:133], v[84:85], v[130:131]
	v_pk_fma_f32 v[88:89], v[150:151], v[88:89], v[148:149]
	v_fma_f32 v212, -v206, v211, 1.0
	v_fmac_f32_e32 v211, v212, v211
	v_div_scale_f32 v212, vcc, v207, v209, v207
	v_mul_f32_e32 v213, v212, v211
	v_fma_f32 v214, -v206, v213, v212
	v_fmac_f32_e32 v213, v214, v211
	v_fma_f32 v206, -v206, v213, v212
	v_div_fmas_f32 v206, v206, v211, v213
	v_div_fixup_f32 v209, v206, v209, v207
	v_mul_f32_e32 v206, 0xbfb8aa3b, v87
	v_exp_f32_e32 v211, v206
	v_pk_fma_f32 v[84:85], v[136:137], v[200:201], v[84:85]
	v_pk_fma_f32 v[88:89], v[152:153], v[198:199], v[88:89]
	v_lshlrev_b32_e32 v199, 16, v43
	v_pk_add_f32 v[206:207], v[210:211], 1.0 op_sel_hi:[1,0]
	v_lshlrev_b32_e32 v198, 16, v42
	v_div_scale_f32 v210, s[0:1], v206, v206, v86
	v_rcp_f32_e32 v211, v210
	v_and_b32_e32 v201, 0xffff0000, v43
	v_and_b32_e32 v200, 0xffff0000, v42
	v_pk_fma_f32 v[88:89], v[156:157], v[200:201], v[88:89]
	v_fma_f32 v212, -v210, v211, 1.0
	v_fmac_f32_e32 v211, v212, v211
	v_div_scale_f32 v212, vcc, v86, v206, v86
	v_mul_f32_e32 v213, v212, v211
	v_fma_f32 v214, -v210, v213, v212
	v_fmac_f32_e32 v213, v214, v211
	v_fma_f32 v210, -v210, v213, v212
	v_div_fmas_f32 v210, v210, v211, v213
	v_div_fixup_f32 v86, v210, v206, v86
	v_div_scale_f32 v206, s[0:1], v207, v207, v87
	v_rcp_f32_e32 v210, v206
	v_lshl_add_u64 v[80:81], v[180:181], 0, s[22:23]
	s_cmpk_lt_u32 s38, 0xffd
	v_fma_f32 v211, -v206, v210, 1.0
	v_fmac_f32_e32 v210, v211, v210
	v_div_scale_f32 v211, vcc, v87, v207, v87
	v_mul_f32_e32 v212, v211, v210
	v_fma_f32 v213, -v206, v212, v211
	v_fmac_f32_e32 v212, v213, v210
	v_fma_f32 v206, -v206, v212, v211
	v_div_fmas_f32 v206, v206, v210, v212
	v_div_fixup_f32 v87, v206, v207, v87
	v_and_b32_sdwa v206, v209, v226 dst_sel:DWORD dst_unused:UNUSED_PAD src0_sel:WORD_1 src1_sel:DWORD
	v_and_b32_sdwa v207, v208, v226 dst_sel:DWORD dst_unused:UNUSED_PAD src0_sel:WORD_1 src1_sel:DWORD
	v_add3_u32 v207, v208, v207, s33
	v_add3_u32 v206, v209, v206, s33
	v_and_b32_sdwa v208, v87, v226 dst_sel:DWORD dst_unused:UNUSED_PAD src0_sel:WORD_1 src1_sel:DWORD
	v_and_b32_sdwa v209, v86, v226 dst_sel:DWORD dst_unused:UNUSED_PAD src0_sel:WORD_1 src1_sel:DWORD
	v_add3_u32 v87, v87, v208, s33
	v_add3_u32 v86, v86, v209, s33
	v_and_b32_e32 v87, 0xffff0000, v87
	v_and_b32_e32 v86, 0xffff0000, v86
	v_or_b32_sdwa v87, v87, v206 dst_sel:DWORD dst_unused:UNUSED_PAD src0_sel:DWORD src1_sel:WORD_1
	v_or_b32_sdwa v86, v86, v207 dst_sel:DWORD dst_unused:UNUSED_PAD src0_sel:DWORD src1_sel:WORD_1
	v_pk_fma_f32 v[206:207], v[134:135], v[198:199], v[84:85]
	v_and_b32_e32 v85, 0xffff0000, v47
	v_and_b32_e32 v84, 0xffff0000, v46
	v_lshlrev_b32_e32 v199, 16, v47
	v_lshlrev_b32_e32 v198, 16, v46
	v_pk_fma_f32 v[88:89], v[158:159], v[84:85], v[88:89]
	v_pk_fma_f32 v[200:201], v[138:139], v[198:199], v[206:207]
	v_mul_f32_e32 v207, 0xbfb8aa3b, v88
	v_mul_f32_e32 v206, 0xbfb8aa3b, v200
	v_exp_f32_e32 v208, v207
	v_mul_f32_e32 v207, 0xbfb8aa3b, v201
	v_exp_f32_e32 v206, v206
	v_exp_f32_e32 v207, v207
	s_nop 0
	v_pk_add_f32 v[206:207], v[206:207], 1.0 op_sel_hi:[1,0]
	s_nop 0
	v_div_scale_f32 v209, s[0:1], v206, v206, v200
	v_rcp_f32_e32 v210, v209
	s_nop 0
	v_fma_f32 v211, -v209, v210, 1.0
	v_fmac_f32_e32 v210, v211, v210
	v_div_scale_f32 v211, vcc, v200, v206, v200
	v_mul_f32_e32 v212, v211, v210
	v_fma_f32 v213, -v209, v212, v211
	v_fmac_f32_e32 v212, v213, v210
	v_fma_f32 v209, -v209, v212, v211
	v_div_fmas_f32 v209, v209, v210, v212
	v_div_fixup_f32 v206, v209, v206, v200
	v_div_scale_f32 v200, s[0:1], v207, v207, v201
; __device__ __forceinline__ float siluf_(float x) { return x / (1.f + __expf(-x)); }
; __device__ __forceinline__ void prep_compute(const PrepRegs& R, const PrepW& W, KP P, int l, int r, int b, int t, int tid, u16* PROJ, u16* XBC, float* DT, u16* ASC, bool dry) {
;     ...
;         float o[8];
; #pragma unroll
;         for (int i = 0; i < 8; ++i) o[i] = siluf_(acc[i]);
;         *(uint4*)(XBC + (long)r * 3072 + c0) = pack8(o);
;         if (t >= L - 3) {
;           float* dst = P->out + O_CVP + ((long)(l * 2 + b) * 3 + (t - (L - 3))) * 3072 + c0;
; #pragma unroll
;           for (int i = 0; i < 8; ++i) dst[i] = raw[i];
;         }
	v_rcp_f32_e32 v209, v200
	s_nop 0
	v_fma_f32 v210, -v200, v209, 1.0
	v_fmac_f32_e32 v209, v210, v209
	v_div_scale_f32 v210, vcc, v201, v207, v201
	v_mul_f32_e32 v211, v210, v209
	v_fma_f32 v212, -v200, v211, v210
	v_fmac_f32_e32 v211, v212, v209
	v_fma_f32 v200, -v200, v211, v210
	v_div_fmas_f32 v200, v200, v209, v211
	v_div_fixup_f32 v207, v200, v207, v201
	v_mul_f32_e32 v200, 0xbfb8aa3b, v89
	v_exp_f32_e32 v209, v200
	s_nop 0
	v_pk_add_f32 v[200:201], v[208:209], 1.0 op_sel_hi:[1,0]
	s_nop 0
	v_div_scale_f32 v208, s[0:1], v200, v200, v88
	v_rcp_f32_e32 v209, v208
	s_nop 0
	v_fma_f32 v210, -v208, v209, 1.0
	v_fmac_f32_e32 v209, v210, v209
	v_div_scale_f32 v210, vcc, v88, v200, v88
	v_mul_f32_e32 v211, v210, v209
	v_fma_f32 v212, -v208, v211, v210
	v_fmac_f32_e32 v211, v212, v209
	v_fma_f32 v208, -v208, v211, v210
	v_div_fmas_f32 v208, v208, v209, v211
	v_div_fixup_f32 v88, v208, v200, v88
	v_div_scale_f32 v200, s[0:1], v201, v201, v89
	v_rcp_f32_e32 v208, v200
	s_nop 0
	v_fma_f32 v209, -v200, v208, 1.0
	v_fmac_f32_e32 v208, v209, v208
	v_div_scale_f32 v209, vcc, v89, v201, v89
	v_mul_f32_e32 v210, v209, v208
	v_fma_f32 v211, -v200, v210, v209
	v_fmac_f32_e32 v210, v211, v208
	v_fma_f32 v200, -v200, v210, v209
	v_div_fmas_f32 v200, v200, v208, v210
	v_div_fixup_f32 v89, v200, v201, v89
	v_and_b32_sdwa v200, v207, v226 dst_sel:DWORD dst_unused:UNUSED_PAD src0_sel:WORD_1 src1_sel:DWORD
	v_and_b32_sdwa v201, v206, v226 dst_sel:DWORD dst_unused:UNUSED_PAD src0_sel:WORD_1 src1_sel:DWORD
	v_add3_u32 v201, v206, v201, s33
	v_add3_u32 v200, v207, v200, s33
	v_and_b32_sdwa v206, v89, v226 dst_sel:DWORD dst_unused:UNUSED_PAD src0_sel:WORD_1 src1_sel:DWORD
	v_and_b32_sdwa v207, v88, v226 dst_sel:DWORD dst_unused:UNUSED_PAD src0_sel:WORD_1 src1_sel:DWORD
	v_add3_u32 v89, v89, v206, s33
	v_add3_u32 v88, v88, v207, s33
	v_and_b32_e32 v89, 0xffff0000, v89
	v_and_b32_e32 v88, 0xffff0000, v88
	v_add_co_u32_e32 v80, vcc, 0x31aa0000, v80
	v_or_b32_sdwa v89, v89, v200 dst_sel:DWORD dst_unused:UNUSED_PAD src0_sel:DWORD src1_sel:WORD_1
	v_or_b32_sdwa v88, v88, v201 dst_sel:DWORD dst_unused:UNUSED_PAD src0_sel:DWORD src1_sel:WORD_1
	v_addc_co_u32_e32 v81, vcc, 0, v81, vcc
	global_store_dwordx4 v[80:81], v[86:89], off sc1
	s_cbranch_scc1 .LBB0_370
	s_load_dwordx2 s[0:1], s[20:21], 0xd0
	s_add_i32 s26, s38, 0xfffff003
	s_add_u32 s26, s26, s46
	s_addc_u32 s39, 0, s47
	s_mulk_i32 s39, 0x3000
	s_mul_hi_u32 s51, s26, 0x3000
	s_add_i32 s51, s51, s39
	s_mulk_i32 s26, 0x3000
	s_waitcnt lgkmcnt(0)
	s_add_u32 s0, s0, s26
	s_addc_u32 s1, s1, s51
	v_lshl_add_u64 v[86:87], v[0:1], 2, s[0:1]
	s_mov_b64 s[0:1], 0x7900000
	v_lshl_add_u64 v[88:89], v[86:87], 0, s[0:1]
	v_add_co_u32_e32 v86, vcc, 0x7900000, v86
	v_mov_b32_e32 v80, v196
	v_mov_b32_e32 v81, v82
	v_mov_b32_e32 v82, v197
	v_addc_co_u32_e32 v87, vcc, 0, v87, vcc
	global_store_dwordx4 v[86:87], v[80:83], off sc1
	s_nop 1
	v_mov_b32_e32 v82, v198
	v_mov_b32_e32 v83, v84
	v_mov_b32_e32 v84, v199
	global_store_dwordx4 v[88:89], v[82:85], off offset:16 sc1
.LBB0_370:
	s_or_b64 exec, exec, s[14:15]
	s_and_saveexec_b64 s[0:1], s[10:11]
	s_xor_b64 s[0:1], exec, s[0:1]
	v_lshlrev_b64 v[88:89], 1, v[166:167]
	s_andn2_saveexec_b64 s[14:15], s[0:1]
	s_cbranch_execz .LBB0_377
	s_waitcnt vmcnt(5)
	v_lshlrev_b32_e32 v89, 16, v49
	v_lshlrev_b32_e32 v88, 16, v48
	s_waitcnt vmcnt(4)
	v_lshlrev_b32_e32 v197, 16, v53
	v_lshlrev_b32_e32 v196, 16, v52
	v_and_b32_e32 v199, 0xffff0000, v49
	v_and_b32_e32 v198, 0xffff0000, v48
	v_and_b32_e32 v201, 0xffff0000, v53
	v_and_b32_e32 v200, 0xffff0000, v52
	v_lshlrev_b32_e32 v214, 16, v56
	v_lshlrev_b32_e32 v215, 16, v57
	v_lshlrev_b32_e32 v222, 16, v60
	v_lshlrev_b32_e32 v223, 16, v61
	s_waitcnt vmcnt(3)
	v_lshlrev_b32_e32 v80, 16, v68
	v_and_b32_e32 v81, 0xffff0000, v68
	s_waitcnt vmcnt(2)
	v_lshlrev_b32_e32 v82, 16, v64
	v_and_b32_e32 v83, 0xffff0000, v64
	v_pk_mul_f32 v[88:89], v[196:197], v[88:89]
	v_and_b32_e32 v216, 0xffff0000, v56
	v_and_b32_e32 v217, 0xffff0000, v57
	v_and_b32_e32 v224, 0xffff0000, v60
	v_and_b32_e32 v225, 0xffff0000, v61
	v_pk_mul_f32 v[80:81], v[82:83], v[80:81]
	v_lshlrev_b32_e32 v82, 16, v69
	v_and_b32_e32 v83, 0xffff0000, v69
	v_lshlrev_b32_e32 v84, 16, v65
	v_and_b32_e32 v85, 0xffff0000, v65
	v_pk_fma_f32 v[88:89], v[104:105], v[88:89], 0 op_sel_hi:[1,1,0]
	v_pk_mul_f32 v[196:197], v[200:201], v[198:199]
	v_pk_mul_f32 v[198:199], v[222:223], v[214:215]
	v_pk_mul_f32 v[82:83], v[84:85], v[82:83]
	v_pk_fma_f32 v[196:197], v[118:119], v[196:197], 0 op_sel_hi:[1,1,0]
	v_pk_fma_f32 v[88:89], v[108:109], v[198:199], v[88:89]
	v_pk_mul_f32 v[198:199], v[224:225], v[216:217]
	s_waitcnt vmcnt(1)
; __device__ __forceinline__ void prep_compute(const PrepRegs& R, const PrepW& W, KP P, int l, int r, int b, int t, int tid, u16* PROJ, u16* XBC, float* DT, u16* ASC, bool dry) {
;     ...
;       if (tid < 256) {
;         const int c0 = tid * 8;
;         float v[8], u[8], a[8], cc[8];
; #pragma unroll
;         for (int i = 0; i < 8; ++i) v[i] = 0.f;
; #pragma unroll
;         for (int j = 0; j < 3; ++j) {
;           unpack8(sa[j], a); unpack8(sc3[j], cc);
;           const float* w = W.sw[j];
; #pragma unroll
;           for (int i = 0; i < 8; ++i) { u[i] = a[i] * cc[i]; v[i] += w[i] * u[i]; }
;         }
;         float sb[8], o[8];
;         unpack8(sbv, sb);
; #pragma unroll
;         for (int i = 0; i < 8; ++i) o[i] = sb[i] * v[i];
;         *(uint4*)(ASC + (long)r * 2048 + c0) = pack8(o);
;         if (t >= L - 2) {
;           float* dst = P->out + O_SCP + ((long)(l * 2 + b) * 2 + (t - (L - 2))) * 2048 + c0;
; #pragma unroll
;           for (int i = 0; i < 8; ++i) dst[i] = u[i];
;         }
	v_and_b32_e32 v201, 0xffff0000, v73
	v_pk_fma_f32 v[196:197], v[124:125], v[198:199], v[196:197]
	v_mov_b32_e32 v198, v80
	v_mov_b32_e32 v199, v82
	v_pk_fma_f32 v[88:89], v[106:107], v[198:199], v[88:89]
	v_mov_b32_e32 v198, v81
	v_mov_b32_e32 v199, v83
	v_pk_fma_f32 v[196:197], v[126:127], v[198:199], v[196:197]
	v_lshlrev_b32_e32 v199, 16, v73
	v_lshlrev_b32_e32 v198, 16, v72
	v_and_b32_e32 v200, 0xffff0000, v72
	v_pk_mul_f32 v[88:89], v[88:89], v[198:199]
	v_pk_mul_f32 v[196:197], v[196:197], v[200:201]
	v_and_b32_sdwa v198, v89, v226 dst_sel:DWORD dst_unused:UNUSED_PAD src0_sel:WORD_1 src1_sel:DWORD
	v_and_b32_sdwa v199, v88, v226 dst_sel:DWORD dst_unused:UNUSED_PAD src0_sel:WORD_1 src1_sel:DWORD
	v_add3_u32 v88, v88, v199, s33
	v_add3_u32 v89, v89, v198, s33
	v_and_b32_sdwa v198, v197, v226 dst_sel:DWORD dst_unused:UNUSED_PAD src0_sel:WORD_1 src1_sel:DWORD
	v_and_b32_sdwa v199, v196, v226 dst_sel:DWORD dst_unused:UNUSED_PAD src0_sel:WORD_1 src1_sel:DWORD
	v_add3_u32 v197, v197, v198, s33
	v_add3_u32 v196, v196, v199, s33
	v_lshlrev_b32_e32 v207, 16, v51
	v_lshlrev_b32_e32 v206, 16, v50
	v_lshlrev_b32_e32 v209, 16, v55
	v_lshlrev_b32_e32 v208, 16, v54
	v_and_b32_e32 v197, 0xffff0000, v197
	v_and_b32_e32 v196, 0xffff0000, v196
	v_and_b32_e32 v211, 0xffff0000, v51
	v_and_b32_e32 v210, 0xffff0000, v50
	v_and_b32_e32 v213, 0xffff0000, v55
	v_and_b32_e32 v212, 0xffff0000, v54
	v_lshlrev_b32_e32 v218, 16, v58
	v_lshlrev_b32_e32 v219, 16, v59
	v_lshlrev_b32_e32 v234, 16, v62
	v_lshlrev_b32_e32 v235, 16, v63
	v_lshlrev_b32_e32 v84, 16, v70
	v_and_b32_e32 v85, 0xffff0000, v70
	v_lshlrev_b32_e32 v86, 16, v66
	v_and_b32_e32 v87, 0xffff0000, v66
	v_or_b32_sdwa v197, v197, v89 dst_sel:DWORD dst_unused:UNUSED_PAD src0_sel:DWORD src1_sel:WORD_1
	v_or_b32_sdwa v196, v196, v88 dst_sel:DWORD dst_unused:UNUSED_PAD src0_sel:DWORD src1_sel:WORD_1
	v_pk_mul_f32 v[88:89], v[208:209], v[206:207]
	v_and_b32_e32 v220, 0xffff0000, v58
	v_and_b32_e32 v221, 0xffff0000, v59
	v_and_b32_e32 v236, 0xffff0000, v62
	v_and_b32_e32 v237, 0xffff0000, v63
	v_pk_mul_f32 v[84:85], v[86:87], v[84:85]
	v_lshlrev_b32_e32 v86, 16, v71
	v_and_b32_e32 v87, 0xffff0000, v71
	v_lshlrev_b32_e32 v238, 16, v67
	v_and_b32_e32 v239, 0xffff0000, v67
	v_pk_fma_f32 v[88:89], v[140:141], v[88:89], 0 op_sel_hi:[1,1,0]
	v_pk_mul_f32 v[198:199], v[212:213], v[210:211]
	v_pk_mul_f32 v[200:201], v[234:235], v[218:219]
	v_pk_mul_f32 v[86:87], v[238:239], v[86:87]
	v_pk_fma_f32 v[198:199], v[154:155], v[198:199], 0 op_sel_hi:[1,1,0]
	v_pk_fma_f32 v[88:89], v[144:145], v[200:201], v[88:89]
	v_pk_mul_f32 v[200:201], v[236:237], v[220:221]
	v_and_b32_e32 v207, 0xffff0000, v75
	v_pk_fma_f32 v[198:199], v[160:161], v[200:201], v[198:199]
	v_mov_b32_e32 v200, v84
	v_mov_b32_e32 v201, v86
	v_pk_fma_f32 v[88:89], v[142:143], v[200:201], v[88:89]
	v_mov_b32_e32 v200, v85
	v_mov_b32_e32 v201, v87
	v_pk_fma_f32 v[198:199], v[162:163], v[200:201], v[198:199]
	v_lshlrev_b32_e32 v201, 16, v75
	v_lshlrev_b32_e32 v200, 16, v74
	v_and_b32_e32 v206, 0xffff0000, v74
	v_pk_mul_f32 v[88:89], v[88:89], v[200:201]
	v_pk_mul_f32 v[198:199], v[198:199], v[206:207]
	v_and_b32_sdwa v201, v88, v226 dst_sel:DWORD dst_unused:UNUSED_PAD src0_sel:WORD_1 src1_sel:DWORD
	v_and_b32_sdwa v200, v89, v226 dst_sel:DWORD dst_unused:UNUSED_PAD src0_sel:WORD_1 src1_sel:DWORD
	v_add3_u32 v88, v88, v201, s33
	v_and_b32_sdwa v201, v198, v226 dst_sel:DWORD dst_unused:UNUSED_PAD src0_sel:WORD_1 src1_sel:DWORD
	v_add3_u32 v89, v89, v200, s33
	v_and_b32_sdwa v200, v199, v226 dst_sel:DWORD dst_unused:UNUSED_PAD src0_sel:WORD_1 src1_sel:DWORD
	v_add3_u32 v198, v198, v201, s33
	v_lshl_add_u64 v[238:239], v[184:185], 0, s[22:23]
	v_add3_u32 v199, v199, v200, s33
	v_and_b32_e32 v198, 0xffff0000, v198
	v_and_b32_e32 v199, 0xffff0000, v199
	v_or_b32_sdwa v198, v198, v88 dst_sel:DWORD dst_unused:UNUSED_PAD src0_sel:DWORD src1_sel:WORD_1
	v_add_co_u32_e32 v88, vcc, 0x36ce4000, v238
	v_or_b32_sdwa v199, v199, v89 dst_sel:DWORD dst_unused:UNUSED_PAD src0_sel:DWORD src1_sel:WORD_1
	s_nop 0
	v_addc_co_u32_e32 v89, vcc, 0, v239, vcc
	s_cmpk_lt_u32 s38, 0xffe
	global_store_dwordx4 v[88:89], v[196:199], off sc1
	s_cbranch_scc1 .LBB0_375
	s_load_dwordx2 s[0:1], s[20:21], 0xd0
	s_add_i32 s26, s38, 0xfffff002
	s_waitcnt lgkmcnt(0)
	s_add_u32 s39, s0, s66
	s_addc_u32 s51, s1, s67
	s_lshl_b64 s[0:1], s[26:27], 13
	s_add_u32 s0, s39, s0
	s_addc_u32 s1, s51, s1
	v_lshl_add_u64 v[88:89], v[0:1], 2, s[0:1]
	s_mov_b64 s[0:1], 0x79b4000
	v_lshl_add_u64 v[196:197], v[88:89], 0, s[0:1]
	v_add_co_u32_e32 v88, vcc, 0x79b4000, v88
	s_nop 1
	v_addc_co_u32_e32 v89, vcc, 0, v89, vcc
	global_store_dwordx4 v[88:89], v[80:83], off sc1
	global_store_dwordx4 v[196:197], v[84:87], off offset:16 sc1
; __device__ __forceinline__ void prep_compute(const PrepRegs& R, const PrepW& W, KP P, int l, int r, int b, int t, int tid, u16* PROJ, u16* XBC, float* DT, u16* ASC, bool dry) {
;     ...
;         if (t >= 3584) {
;           float vv[8];
;           unpack8(*(const uint4*)(pr + OV + c0), vv);
;           float* dst = P->out + O_VP + ((long)(l * 2 + b) * 512 + (t - 3584)) * 2048 + c0;
; #pragma unroll
;           for (int i = 0; i < 8; ++i) dst[i] = vv[i];
;         }
;       }
;       {
;         const int e0 = tid * 8;
;         float x[8];
;         unpack8(qk, x);
;         float ss = 0.f;
; #pragma unroll
;         for (int i = 0; i < 8; ++i) ss += x[i] * x[i];
;         ss += sx<1>(ss); ss += sx<2>(ss); ss += sx<4>(ss); ss += sx<8>(ss);
;         const float rstd = rsqrtf(ss * (1.f / 128.f) + EPS);
;         const bool isK = e0 >= 2048;
;         const float* g = W.qg;
;         float y[8];
; #pragma unroll
;         for (int i = 0; i < 8; ++i) y[i] = x[i] * rstd * g[i];
;         if (!dry) *(uint4*)(pr + OQ + e0) = pack8(y);
;         if (isK && t >= 3584) {
;           float* dst = P->out + O_KP + ((long)(l * 2 + b) * 512 + (t - 3584)) * 2048 + (e0 - 2048);
; #pragma unroll
;           for (int i = 0; i < 8; ++i) dst[i] = y[i];
;         }
;       }
.LBB0_375:
	s_cmpk_lt_u32 s38, 0xe00
	v_mov_b64_e32 v[88:89], v[168:169]
	s_cbranch_scc1 .LBB0_377
	v_lshl_add_u64 v[80:81], v[186:187], 0, s[22:23]
	global_load_dwordx4 v[80:83], v[80:81], off
	s_load_dwordx2 s[0:1], s[20:21], 0xd0
	s_waitcnt lgkmcnt(0)
	v_lshl_add_u64 v[84:85], s[0:1], 0, v[194:195]
	v_lshl_add_u64 v[88:89], v[84:85], 0, s[42:43]
	s_waitcnt vmcnt(0)
	v_lshlrev_b32_e32 v198, 16, v83
	v_lshlrev_b32_e32 v196, 16, v82
	v_and_b32_e32 v199, 0xffff0000, v83
	v_and_b32_e32 v197, 0xffff0000, v82
	v_lshlrev_b32_e32 v86, 16, v81
	v_lshlrev_b32_e32 v84, 16, v80
	v_and_b32_e32 v87, 0xffff0000, v81
	v_and_b32_e32 v85, 0xffff0000, v80
	global_store_dwordx4 v[88:89], v[196:199], off offset:16 sc1
	global_store_dwordx4 v[88:89], v[84:87], off sc1
	v_mov_b64_e32 v[88:89], v[168:169]
.LBB0_377:
	s_or_b64 exec, exec, s[14:15]
	s_waitcnt vmcnt(0)
	v_lshlrev_b32_e32 v80, 16, v76
	v_and_b32_e32 v81, 0xffff0000, v76
	v_pk_mul_f32 v[82:83], v[80:81], v[80:81]
	v_lshlrev_b32_e32 v86, 16, v77
	v_and_b32_e32 v87, 0xffff0000, v77
	v_pk_mul_f32 v[84:85], v[86:87], v[86:87]
	v_add_f32_e32 v82, v82, v83
	v_lshlrev_b32_e32 v196, 16, v78
	v_and_b32_e32 v197, 0xffff0000, v78
	v_add_f32_e32 v82, v84, v82
	v_pk_mul_f32 v[198:199], v[196:197], v[196:197]
	v_add_f32_e32 v82, v85, v82
	v_lshlrev_b32_e32 v200, 16, v79
	v_and_b32_e32 v201, 0xffff0000, v79
	v_add_f32_e32 v82, v198, v82
	v_pk_mul_f32 v[206:207], v[200:201], v[200:201]
	v_add_f32_e32 v82, v199, v82
	v_add_f32_e32 v82, v206, v82
	v_add_f32_e32 v82, v207, v82
	ds_swizzle_b32 v83, v82 offset:swizzle(SWAP,1)
	s_add_u32 s0, s49, s22
	s_addc_u32 s1, s50, s23
	s_cmpk_gt_u32 s38, 0xdff
	v_lshl_add_u64 v[88:89], s[0:1], 0, v[88:89]
	s_waitcnt lgkmcnt(0)
	v_add_f32_e32 v82, v82, v83
	ds_swizzle_b32 v83, v82 offset:swizzle(SWAP,2)
	s_cselect_b64 s[0:1], -1, 0
	s_and_b64 s[14:15], s[4:5], s[0:1]
	s_waitcnt lgkmcnt(0)
	v_add_f32_e32 v82, v82, v83
	ds_swizzle_b32 v83, v82 offset:swizzle(SWAP,4)
	s_waitcnt lgkmcnt(0)
	v_add_f32_e32 v82, v82, v83
	ds_swizzle_b32 v83, v82 offset:swizzle(SWAP,8)
	s_waitcnt lgkmcnt(0)
	v_add_f32_e32 v82, v82, v83
	v_fmamk_f32 v82, v82, 0x3c000000, v189
	v_cmp_gt_f32_e32 vcc, s62, v82
	v_mul_f32_e32 v83, 0x4b800000, v82
	s_nop 0
	v_cndmask_b32_e32 v82, v82, v83, vcc
	v_rsq_f32_e32 v82, v82
	s_nop 0
	v_mul_f32_e32 v83, 0x45800000, v82
	v_cndmask_b32_e32 v82, v82, v83, vcc
	v_pk_mul_f32 v[80:81], v[82:83], v[80:81] op_sel_hi:[0,1]
	v_pk_mul_f32 v[84:85], v[110:111], v[80:81]
	v_pk_mul_f32 v[80:81], v[82:83], v[86:87] op_sel_hi:[0,1]
	v_pk_mul_f32 v[86:87], v[128:129], v[80:81]
	v_pk_mul_f32 v[80:81], v[82:83], v[196:197] op_sel_hi:[0,1]
	v_and_b32_sdwa v197, v84, v226 dst_sel:DWORD dst_unused:UNUSED_PAD src0_sel:WORD_1 src1_sel:DWORD
	v_add3_u32 v198, v84, v197, s33
	v_and_b32_sdwa v197, v87, v226 dst_sel:DWORD dst_unused:UNUSED_PAD src0_sel:WORD_1 src1_sel:DWORD
	v_and_b32_sdwa v199, v85, v226 dst_sel:DWORD dst_unused:UNUSED_PAD src0_sel:WORD_1 src1_sel:DWORD
	v_and_b32_sdwa v196, v86, v226 dst_sel:DWORD dst_unused:UNUSED_PAD src0_sel:WORD_1 src1_sel:DWORD
	v_add3_u32 v197, v87, v197, s33
	v_add3_u32 v199, v85, v199, s33
	v_pk_mul_f32 v[80:81], v[146:147], v[80:81]
	v_pk_mul_f32 v[82:83], v[82:83], v[200:201] op_sel_hi:[0,1]
	v_add3_u32 v196, v86, v196, s33
	v_and_b32_e32 v197, 0xffff0000, v197
	v_and_b32_e32 v199, 0xffff0000, v199
	v_pk_mul_f32 v[82:83], v[164:165], v[82:83]
	v_or_b32_sdwa v197, v197, v196 dst_sel:DWORD dst_unused:UNUSED_PAD src0_sel:DWORD src1_sel:WORD_1
	v_or_b32_sdwa v196, v199, v198 dst_sel:DWORD dst_unused:UNUSED_PAD src0_sel:DWORD src1_sel:WORD_1
	v_and_b32_sdwa v199, v80, v226 dst_sel:DWORD dst_unused:UNUSED_PAD src0_sel:WORD_1 src1_sel:DWORD
	v_add3_u32 v200, v80, v199, s33
	v_and_b32_sdwa v199, v83, v226 dst_sel:DWORD dst_unused:UNUSED_PAD src0_sel:WORD_1 src1_sel:DWORD
	v_and_b32_sdwa v201, v81, v226 dst_sel:DWORD dst_unused:UNUSED_PAD src0_sel:WORD_1 src1_sel:DWORD
	v_and_b32_sdwa v198, v82, v226 dst_sel:DWORD dst_unused:UNUSED_PAD src0_sel:WORD_1 src1_sel:DWORD
	v_add3_u32 v199, v83, v199, s33
	v_add3_u32 v201, v81, v201, s33
	v_add3_u32 v198, v82, v198, s33
	v_and_b32_e32 v199, 0xffff0000, v199
	v_and_b32_e32 v201, 0xffff0000, v201
	v_or_b32_sdwa v199, v199, v198 dst_sel:DWORD dst_unused:UNUSED_PAD src0_sel:DWORD src1_sel:WORD_1
	v_or_b32_sdwa v198, v201, v200 dst_sel:DWORD dst_unused:UNUSED_PAD src0_sel:DWORD src1_sel:WORD_1
	global_store_dwordx4 v[88:89], v[196:199], off offset:-8 sc1
	s_and_saveexec_b64 s[0:1], s[14:15]
	s_cbranch_execz .LBB0_379
	s_load_dwordx2 s[14:15], s[20:21], 0xd0
	s_waitcnt lgkmcnt(0)
	v_lshl_add_u64 v[88:89], s[14:15], 0, v[192:193]
	v_lshl_add_u64 v[88:89], v[88:89], 0, s[42:43]
	v_add_co_u32_e32 v88, vcc, 0x40fe000, v88
	s_nop 1
	v_addc_co_u32_e32 v89, vcc, 0, v89, vcc
	global_store_dwordx4 v[88:89], v[84:87], off sc1
	global_store_dwordx4 v[88:89], v[80:83], off offset:16 sc1

; __device__ __forceinline__ float siluf_(float x) { return x / (1.f + __expf(-x)); }
; __device__ __forceinline__ void prep_phase(KP P, int l, bool dry) {
;     ...
;     if (tid < 384) {
;       const int c0 = tid * 8;
;       float acc[8], cur[8];
; #pragma unroll
;       for (int i = 0; i < 8; ++i) { acc[i] = P->conv_b[l * 3072 + c0 + i]; cur[i] = 0.f; }
; #pragma unroll
;       for (int j = 0; j < 4; ++j) {
;         const int tt = t - 3 + j;
;         float raw[8];
;         if (tt >= 0) {
;           unpack8(*(const uint4*)(PROJ + (long)(r - 3 + j) * NC + OXBC + c0), raw);
;         } else if (isS) {
;           const float* s = P->st_conv + ((long)(l * 8 + b) * 3 + (tt + 3)) * 3072 + c0;
;           const float4 s0 = *(const float4*)s, s1 = *(const float4*)(s + 4);
;           raw[0] = s0.x; raw[1] = s0.y; raw[2] = s0.z; raw[3] = s0.w; raw[4] = s1.x; raw[5] = s1.y; raw[6] = s1.z; raw[7] = s1.w;
;         } else {
; #pragma unroll
;           for (int i = 0; i < 8; ++i) raw[i] = 0.f;
;         }
;         const float* w = P->conv_w + ((long)l * 4 + j) * 3072 + c0;
; #pragma unroll
;         for (int i = 0; i < 8; ++i) { acc[i] += w[i] * raw[i]; if (j == 3) cur[i] = raw[i]; }
;       }
;       float o[8];
; #pragma unroll
;       for (int i = 0; i < 8; ++i) o[i] = siluf_(acc[i]);
;       *(uint4*)(XBC + (long)r * 3072 + c0) = pack8(o);
.LBB0_406:
	s_waitcnt vmcnt(4)
	v_mov_b32_e32 v10, v28
	v_mov_b32_e32 v11, v30
	s_waitcnt vmcnt(2)
	v_mov_b32_e32 v22, v36
	v_mov_b32_e32 v23, v38
	v_mov_b32_e32 v30, v29
	v_mov_b32_e32 v38, v37
	v_mov_b32_e32 v28, v16
	v_mov_b32_e32 v29, v18
	v_mov_b32_e32 v18, v17
	v_pk_fma_f32 v[10:11], v[10:11], v[22:23], v[28:29]
	v_pk_fma_f32 v[16:17], v[30:31], v[38:39], v[18:19]
	v_mov_b32_e32 v19, v26
	v_mov_b32_e32 v23, v34
	v_mov_b32_e32 v26, v25
	v_mov_b32_e32 v34, v33
	v_mov_b32_e32 v25, v14
	v_mov_b32_e32 v14, v13
	v_mov_b32_e32 v18, v24
	v_mov_b32_e32 v22, v32
	v_mov_b32_e32 v24, v12
	v_pk_fma_f32 v[12:13], v[26:27], v[34:35], v[14:15]
	s_waitcnt vmcnt(1)
	v_mov_b32_e32 v14, v52
	v_mov_b32_e32 v15, v54
	v_pk_fma_f32 v[18:19], v[18:19], v[22:23], v[24:25]
	v_mov_b32_e32 v54, v53
	v_pk_fma_f32 v[32:33], v[72:73], v[14:15], v[10:11]
	s_waitcnt vmcnt(0)
	v_mov_b32_e32 v10, v48
	v_mov_b32_e32 v11, v50
	s_mov_b64 s[0:1], 0x6000
	v_pk_fma_f32 v[22:23], v[46:47], v[54:55], v[16:17]
	v_pk_fma_f32 v[30:31], v[70:71], v[10:11], v[18:19]
	v_lshl_add_u64 v[16:17], v[68:69], 0, s[0:1]
	v_lshl_add_u64 v[10:11], v[0:1], 1, s[10:11]
	s_movk_i32 s0, 0x1000
	v_add_co_u32_e32 v10, vcc, s0, v10
	v_mov_b32_e32 v50, v49
	s_nop 0
	v_addc_co_u32_e32 v11, vcc, 0, v11, vcc
	v_pk_fma_f32 v[28:29], v[42:43], v[50:51], v[12:13]
	global_load_dwordx4 v[10:13], v[10:11], off
	s_mov_b64 s[0:1], 0x9000
	v_lshl_add_u64 v[38:39], v[68:69], 0, s[0:1]
	s_cmp_lt_u32 s38, 13
	s_waitcnt vmcnt(0)
	v_lshlrev_b32_e32 v27, 16, v13
	v_lshlrev_b32_e32 v26, 16, v12
	v_and_b32_e32 v15, 0xffff0000, v13
	v_and_b32_e32 v14, 0xffff0000, v12
	v_mad_i64_i32 v[12:13], s[0:1], s22, v229, v[56:57]
	s_movk_i32 s0, 0x6000
	s_nop 0
	v_add_co_u32_e32 v18, vcc, s0, v68
	s_mov_b32 s0, 0x9000
	s_nop 0
	v_addc_co_u32_e32 v19, vcc, 0, v69, vcc
	global_load_dwordx4 v[34:37], v[18:19], off
	s_nop 0
	global_load_dwordx4 v[16:19], v[16:17], off offset:16
	v_lshlrev_b32_e32 v25, 16, v11
	v_lshlrev_b32_e32 v24, 16, v10
	v_and_b32_e32 v11, 0xffff0000, v11
	v_and_b32_e32 v10, 0xffff0000, v10
	s_waitcnt vmcnt(1)
	v_mov_b32_e32 v42, v34
	v_mov_b32_e32 v43, v36
	v_pk_fma_f32 v[42:43], v[20:21], v[42:43], v[32:33]
	v_add_co_u32_e32 v20, vcc, s0, v68
	v_mov_b32_e32 v36, v35
	s_nop 0
	v_addc_co_u32_e32 v21, vcc, 0, v69, vcc
	v_pk_fma_f32 v[36:37], v[44:45], v[36:37], v[22:23]
	global_load_dwordx4 v[32:35], v[20:21], off
	s_nop 0
	global_load_dwordx4 v[20:23], v[38:39], off offset:16
	s_waitcnt vmcnt(1)
	v_mov_b32_e32 v39, v34
	v_mov_b32_e32 v34, v33
	v_mov_b32_e32 v38, v32
	v_pk_fma_f32 v[32:33], v[34:35], v[10:11], v[36:37]
	v_pk_fma_f32 v[38:39], v[38:39], v[24:25], v[42:43]
	v_mul_f32_e32 v35, 0xbfb8aa3b, v32
	v_mul_f32_e32 v34, 0xbfb8aa3b, v38
	v_exp_f32_e32 v36, v35
	v_mul_f32_e32 v35, 0xbfb8aa3b, v39
	v_exp_f32_e32 v34, v34
	v_exp_f32_e32 v35, v35
	s_nop 0
	v_pk_add_f32 v[34:35], v[34:35], 1.0 op_sel_hi:[1,0]
	s_nop 0
	v_div_scale_f32 v37, s[0:1], v34, v34, v38
	v_rcp_f32_e32 v42, v37
	s_nop 0
	v_fma_f32 v43, -v37, v42, 1.0
	v_fmac_f32_e32 v42, v43, v42
	v_div_scale_f32 v43, vcc, v38, v34, v38
	v_mul_f32_e32 v44, v43, v42
	v_fma_f32 v45, -v37, v44, v43
	v_fmac_f32_e32 v44, v45, v42
	v_fma_f32 v37, -v37, v44, v43
	v_div_fmas_f32 v37, v37, v42, v44
	v_div_fixup_f32 v38, v37, v34, v38
	v_div_scale_f32 v34, s[0:1], v35, v35, v39
	v_rcp_f32_e32 v37, v34
	s_nop 0
	v_fma_f32 v42, -v34, v37, 1.0
	v_fmac_f32_e32 v37, v42, v37
	v_div_scale_f32 v42, vcc, v39, v35, v39
	v_mul_f32_e32 v43, v42, v37
	v_fma_f32 v44, -v34, v43, v42
	v_fmac_f32_e32 v43, v44, v37
	v_fma_f32 v34, -v34, v43, v42
	v_div_fmas_f32 v34, v34, v37, v43
	v_div_fixup_f32 v39, v34, v35, v39
	v_mul_f32_e32 v34, 0xbfb8aa3b, v33
	v_exp_f32_e32 v37, v34
	s_nop 0
	v_pk_add_f32 v[34:35], v[36:37], 1.0 op_sel_hi:[1,0]
	s_nop 0
	v_div_scale_f32 v36, s[0:1], v34, v34, v32
	v_rcp_f32_e32 v37, v36
	s_nop 0
	v_fma_f32 v42, -v36, v37, 1.0
	v_fmac_f32_e32 v37, v42, v37
	v_div_scale_f32 v42, vcc, v32, v34, v32
	v_mul_f32_e32 v43, v42, v37
	v_fma_f32 v44, -v36, v43, v42
	v_fmac_f32_e32 v43, v44, v37
	v_fma_f32 v36, -v36, v43, v42
	v_div_fmas_f32 v36, v36, v37, v43
	v_div_fixup_f32 v32, v36, v34, v32
	v_div_scale_f32 v34, s[0:1], v35, v35, v33
	v_rcp_f32_e32 v36, v34
	s_nop 0
	v_fma_f32 v37, -v34, v36, 1.0
	v_fmac_f32_e32 v36, v37, v36
	v_div_scale_f32 v37, vcc, v33, v35, v33
	v_mul_f32_e32 v42, v37, v36
	v_fma_f32 v43, -v34, v42, v37
	v_fmac_f32_e32 v42, v43, v36
	v_fma_f32 v34, -v34, v42, v37
	v_div_fmas_f32 v34, v34, v36, v42
	v_div_fixup_f32 v33, v34, v35, v33
	v_and_b32_sdwa v37, v32, v226 dst_sel:DWORD dst_unused:UNUSED_PAD src0_sel:WORD_1 src1_sel:DWORD
	v_and_b32_sdwa v35, v38, v226 dst_sel:DWORD dst_unused:UNUSED_PAD src0_sel:WORD_1 src1_sel:DWORD
	v_and_b32_sdwa v36, v33, v226 dst_sel:DWORD dst_unused:UNUSED_PAD src0_sel:WORD_1 src1_sel:DWORD
	v_add3_u32 v32, v32, v37, s33
	v_and_b32_sdwa v34, v39, v226 dst_sel:DWORD dst_unused:UNUSED_PAD src0_sel:WORD_1 src1_sel:DWORD
	v_add3_u32 v35, v38, v35, s33
	v_add3_u32 v33, v33, v36, s33
	v_and_b32_e32 v32, 0xffff0000, v32
	v_add3_u32 v34, v39, v34, s33
	v_and_b32_e32 v33, 0xffff0000, v33
	v_or_b32_sdwa v32, v32, v35 dst_sel:DWORD dst_unused:UNUSED_PAD src0_sel:DWORD src1_sel:WORD_1
	v_mov_b32_e32 v35, v18
	v_mov_b32_e32 v18, v17
	v_or_b32_sdwa v33, v33, v34 dst_sel:DWORD dst_unused:UNUSED_PAD src0_sel:DWORD src1_sel:WORD_1
	v_mov_b32_e32 v34, v16
	v_pk_fma_f32 v[16:17], v[40:41], v[18:19], v[28:29]
	s_waitcnt vmcnt(0)
; __device__ __forceinline__ float siluf_(float x) { return x / (1.f + __expf(-x)); }
; __device__ __forceinline__ void prep_phase(KP P, int l, bool dry) {
;     ...
;       float o[8];
; #pragma unroll
;       for (int i = 0; i < 8; ++i) o[i] = siluf_(acc[i]);
;       *(uint4*)(XBC + (long)r * 3072 + c0) = pack8(o);
;       if (t >= L - 3) {
;         float* dst = isS ? P->out + O_CVS + ((long)(l * 8 + b) * 3 + (t - (L - 3))) * 3072 + c0
;                          : P->out + O_CVP + ((long)(l * 2 + b) * 3 + (t - (L - 3))) * 3072 + c0;
; #pragma unroll
;         for (int i = 0; i < 8; ++i) dst[i] = cur[i];
;       }
	v_mov_b32_e32 v19, v22
	v_mov_b32_e32 v22, v21
	v_pk_fma_f32 v[8:9], v[8:9], v[34:35], v[30:31]
	v_mov_b32_e32 v18, v20
	v_pk_fma_f32 v[16:17], v[22:23], v[14:15], v[16:17]
	v_pk_fma_f32 v[8:9], v[18:19], v[26:27], v[8:9]
	v_mul_f32_e32 v19, 0xbfb8aa3b, v16
	v_mul_f32_e32 v18, 0xbfb8aa3b, v8
	v_exp_f32_e32 v20, v19
	v_mul_f32_e32 v19, 0xbfb8aa3b, v9
	v_exp_f32_e32 v18, v18
	v_exp_f32_e32 v19, v19
	s_nop 0
	v_pk_add_f32 v[18:19], v[18:19], 1.0 op_sel_hi:[1,0]
	s_nop 0
	v_div_scale_f32 v21, s[0:1], v18, v18, v8
	v_rcp_f32_e32 v22, v21
	s_nop 0
	v_fma_f32 v23, -v21, v22, 1.0
	v_fmac_f32_e32 v22, v23, v22
	v_div_scale_f32 v23, vcc, v8, v18, v8
	v_mul_f32_e32 v28, v23, v22
	v_fma_f32 v29, -v21, v28, v23
	v_fmac_f32_e32 v28, v29, v22
	v_fma_f32 v21, -v21, v28, v23
	v_div_fmas_f32 v21, v21, v22, v28
	v_div_fixup_f32 v18, v21, v18, v8
	v_div_scale_f32 v8, s[0:1], v19, v19, v9
	v_rcp_f32_e32 v21, v8
	s_nop 0
	v_fma_f32 v22, -v8, v21, 1.0
	v_fmac_f32_e32 v21, v22, v21
	v_div_scale_f32 v22, vcc, v9, v19, v9
	v_mul_f32_e32 v23, v22, v21
	v_fma_f32 v28, -v8, v23, v22
	v_fmac_f32_e32 v23, v28, v21
	v_fma_f32 v8, -v8, v23, v22
	v_div_fmas_f32 v8, v8, v21, v23
	v_div_fixup_f32 v19, v8, v19, v9
	v_mul_f32_e32 v8, 0xbfb8aa3b, v17
	v_exp_f32_e32 v21, v8
	s_nop 0
	v_pk_add_f32 v[8:9], v[20:21], 1.0 op_sel_hi:[1,0]
	s_nop 0
	v_div_scale_f32 v20, s[0:1], v8, v8, v16
	v_rcp_f32_e32 v21, v20
	s_nop 0
	v_fma_f32 v22, -v20, v21, 1.0
	v_fmac_f32_e32 v21, v22, v21
	v_div_scale_f32 v22, vcc, v16, v8, v16
	v_mul_f32_e32 v23, v22, v21
	v_fma_f32 v28, -v20, v23, v22
	v_fmac_f32_e32 v23, v28, v21
	v_fma_f32 v20, -v20, v23, v22
	v_div_fmas_f32 v20, v20, v21, v23
	v_div_fixup_f32 v8, v20, v8, v16
	v_div_scale_f32 v16, s[0:1], v9, v9, v17
	v_rcp_f32_e32 v20, v16
	s_nop 0
	v_fma_f32 v21, -v16, v20, 1.0
	v_fmac_f32_e32 v20, v21, v20
	v_div_scale_f32 v21, vcc, v17, v9, v17
	v_mul_f32_e32 v22, v21, v20
	v_fma_f32 v23, -v16, v22, v21
	v_fmac_f32_e32 v22, v23, v20
	v_fma_f32 v16, -v16, v22, v21
	v_div_fmas_f32 v16, v16, v20, v22
	v_div_fixup_f32 v9, v16, v9, v17
	v_and_b32_sdwa v16, v19, v226 dst_sel:DWORD dst_unused:UNUSED_PAD src0_sel:WORD_1 src1_sel:DWORD
	v_and_b32_sdwa v17, v18, v226 dst_sel:DWORD dst_unused:UNUSED_PAD src0_sel:WORD_1 src1_sel:DWORD
	v_add3_u32 v17, v18, v17, s33
	v_add3_u32 v16, v19, v16, s33
	v_and_b32_sdwa v18, v9, v226 dst_sel:DWORD dst_unused:UNUSED_PAD src0_sel:WORD_1 src1_sel:DWORD
	v_and_b32_sdwa v19, v8, v226 dst_sel:DWORD dst_unused:UNUSED_PAD src0_sel:WORD_1 src1_sel:DWORD
	v_add3_u32 v9, v9, v18, s33
	v_add3_u32 v8, v8, v19, s33
	v_and_b32_e32 v9, 0xffff0000, v9
	v_and_b32_e32 v8, 0xffff0000, v8
	v_or_b32_sdwa v35, v9, v16 dst_sel:DWORD dst_unused:UNUSED_PAD src0_sel:DWORD src1_sel:WORD_1
	v_or_b32_sdwa v34, v8, v17 dst_sel:DWORD dst_unused:UNUSED_PAD src0_sel:DWORD src1_sel:WORD_1
	global_store_dwordx4 v[12:13], v[32:35], off sc1
	s_cbranch_scc1 .LBB0_408
	s_load_dwordx2 s[0:1], s[20:21], 0xd0
	s_add_i32 s12, s38, -13
	s_add_u32 s12, s14, s12
	s_addc_u32 s13, s15, 0
	s_mulk_i32 s13, 0x3000
	s_mul_hi_u32 s14, s12, 0x3000
	s_add_i32 s14, s14, s13
	s_mulk_i32 s12, 0x3000
	s_waitcnt lgkmcnt(0)
	s_add_u32 s0, s0, s12
	s_addc_u32 s1, s1, s14
	v_lshl_add_u64 v[16:17], v[0:1], 2, s[0:1]
	s_mov_b64 s[0:1], 0x7924000
	v_lshl_add_u64 v[8:9], v[16:17], 0, s[0:1]
	v_mov_b32_e32 v12, v26
	v_mov_b32_e32 v13, v14
	v_mov_b32_e32 v14, v27
	global_store_dwordx4 v[8:9], v[12:15], off offset:16 sc1
	v_mov_b32_e32 v8, v24
	v_mov_b32_e32 v9, v10
	v_add_co_u32_e32 v12, vcc, 0x7924000, v16
	v_mov_b32_e32 v10, v25
	s_nop 0
	v_addc_co_u32_e32 v13, vcc, 0, v17, vcc
	global_store_dwordx4 v[12:13], v[8:11], off sc1

; __device__ __forceinline__ void prep_phase(KP P, int l, bool dry) {
;     ...
;     if (tid < 256) {
;       const int c0 = tid * 8;
;       float v[8], ucur[8];
; #pragma unroll
;       for (int i = 0; i < 8; ++i) { v[i] = 0.f; ucur[i] = 0.f; }
; #pragma unroll
;       for (int j = 0; j < 3; ++j) {
;         const int tt = t - 2 + j;
;         float u[8];
;         if (tt >= 0) {
;           float a[8], c[8];
;           unpack8(*(const uint4*)(PROJ + (long)(r - 2 + j) * NC + OSC + c0), a);
;           unpack8(*(const uint4*)(PROJ + (long)(r - 2 + j) * NC + OSH + c0), c);
; #pragma unroll
;           for (int i = 0; i < 8; ++i) u[i] = a[i] * c[i];
;         } else if (isS) {
;           const float* s = P->st_sc + ((long)(l * 8 + b) * 2 + (tt + 2)) * 2048 + c0;
; #pragma unroll
;           for (int i = 0; i < 8; ++i) u[i] = s[i];
;         } else {
; #pragma unroll
;           for (int i = 0; i < 8; ++i) u[i] = 0.f;
;         }
;         const float* w = P->sc_conv_w + ((long)l * 3 + j) * 2048 + c0;
; #pragma unroll
;         for (int i = 0; i < 8; ++i) { v[i] += w[i] * u[i]; if (j == 2) ucur[i] = u[i]; }
;       }
;       float sb[8], o[8];
;       unpack8(*(const uint4*)(pr + OSB + c0), sb);
; #pragma unroll
;       for (int i = 0; i < 8; ++i) o[i] = sb[i] * v[i];
;       *(uint4*)(ASC + (long)r * 2048 + c0) = pack8(o);
;       if (t >= L - 2) {
;         float* dst = isS ? P->out + O_SCS + ((long)(l * 8 + b) * 2 + (t - (L - 2))) * 2048 + c0
;                          : P->out + O_SCP + ((long)(l * 2 + b) * 2 + (t - (L - 2))) * 2048 + c0;
; #pragma unroll
;         for (int i = 0; i < 8; ++i) dst[i] = ucur[i];
;       }
.LBB0_416:
	s_waitcnt vmcnt(0)
	v_mov_b32_e32 v10, v26
	v_mov_b32_e32 v11, v28
	v_mov_b32_e32 v28, v27
	v_pk_fma_f32 v[26:27], v[14:15], v[10:11], 0 op_sel_hi:[1,1,0]
	v_mov_b32_e32 v10, v18
	v_mov_b32_e32 v11, v20
	s_mov_b64 s[0:1], 0x2000
	v_mov_b32_e32 v20, v19
	v_pk_fma_f32 v[36:37], v[32:33], v[10:11], 0 op_sel_hi:[1,1,0]
	v_lshl_add_u64 v[18:19], v[40:41], 0, s[0:1]
	v_lshl_add_u64 v[32:33], v[0:1], 1, s[10:11]
	s_movk_i32 s0, 0x3000
	v_add_co_u32_e32 v10, vcc, s0, v32
	v_pk_fma_f32 v[24:25], v[12:13], v[28:29], 0 op_sel_hi:[1,1,0]
	s_nop 0
	v_addc_co_u32_e32 v11, vcc, 0, v33, vcc
	global_load_dwordx4 v[10:13], v[10:11], off offset:2048
	s_movk_i32 s18, 0x4000
	v_pk_fma_f32 v[34:35], v[16:17], v[20:21], 0 op_sel_hi:[1,1,0]
	s_mov_b64 s[0:1], 0x4000
	v_lshl_add_u64 v[48:49], v[40:41], 0, s[0:1]
	s_lshl_b64 s[0:1], s[22:23], 12
	s_cmp_lt_u32 s38, 14
	s_waitcnt vmcnt(0)
	v_lshlrev_b32_e32 v14, 16, v10
	v_and_b32_e32 v15, 0xffff0000, v10
	v_add_co_u32_e32 v10, vcc, s18, v32
	v_lshlrev_b32_e32 v16, 16, v11
	v_and_b32_e32 v17, 0xffff0000, v11
	v_addc_co_u32_e32 v11, vcc, 0, v33, vcc
	v_lshlrev_b32_e32 v20, 16, v12
	v_and_b32_e32 v21, 0xffff0000, v12
	v_lshlrev_b32_e32 v28, 16, v13
	v_and_b32_e32 v29, 0xffff0000, v13
	global_load_dwordx4 v[10:13], v[10:11], off offset:2048
	s_waitcnt vmcnt(0)
	v_lshlrev_b32_e32 v38, 16, v10
	v_and_b32_e32 v39, 0xffff0000, v10
	v_lshlrev_b32_e32 v10, 16, v11
	v_and_b32_e32 v11, 0xffff0000, v11
	v_lshlrev_b32_e32 v44, 16, v12
	v_and_b32_e32 v45, 0xffff0000, v12
	v_pk_mul_f32 v[14:15], v[14:15], v[38:39]
	v_lshl_add_u64 v[38:39], v[58:59], 0, s[0:1]
	s_movk_i32 s0, 0x2000
	v_pk_mul_f32 v[16:17], v[16:17], v[10:11]
	v_pk_mul_f32 v[10:11], v[20:21], v[44:45]
	v_add_co_u32_e32 v20, vcc, s0, v40
	v_lshlrev_b32_e32 v12, 16, v13
	s_nop 0
	v_addc_co_u32_e32 v21, vcc, 0, v41, vcc
	global_load_dwordx4 v[44:47], v[20:21], off
	s_nop 0
	global_load_dwordx4 v[18:21], v[18:19], off offset:16
	v_and_b32_e32 v13, 0xffff0000, v13
	v_pk_mul_f32 v[12:13], v[28:29], v[12:13]
	s_waitcnt vmcnt(1)
	v_mov_b32_e32 v28, v44
	v_mov_b32_e32 v29, v46
	v_pk_fma_f32 v[50:51], v[22:23], v[28:29], v[26:27]
	v_add_co_u32_e32 v22, vcc, s18, v40
	v_mov_b32_e32 v46, v45
	s_nop 0
	v_addc_co_u32_e32 v23, vcc, 0, v41, vcc
	v_pk_fma_f32 v[42:43], v[42:43], v[46:47], v[24:25]
	global_load_dwordx4 v[26:29], v[22:23], off
	s_nop 0
	global_load_dwordx4 v[22:25], v[48:49], off offset:16
	v_mov_b32_e32 v40, v14
	v_mov_b32_e32 v41, v16
	s_waitcnt vmcnt(1)
	v_mov_b32_e32 v44, v26
	v_mov_b32_e32 v45, v28
	v_add_co_u32_e32 v26, vcc, s0, v32
	v_pk_fma_f32 v[40:41], v[40:41], v[44:45], v[50:51]
	v_mov_b32_e32 v44, v15
	v_mov_b32_e32 v45, v17
	v_mov_b32_e32 v28, v27
	v_addc_co_u32_e32 v27, vcc, 0, v33, vcc
	v_pk_fma_f32 v[42:43], v[44:45], v[28:29], v[42:43]
	global_load_dwordx4 v[26:29], v[26:27], off offset:2048
	s_waitcnt vmcnt(0)
	v_lshlrev_b32_e32 v45, 16, v27
	v_lshlrev_b32_e32 v44, 16, v26
	v_and_b32_e32 v27, 0xffff0000, v27
	v_and_b32_e32 v26, 0xffff0000, v26
	v_pk_mul_f32 v[40:41], v[40:41], v[44:45]
	v_pk_mul_f32 v[26:27], v[42:43], v[26:27]
	v_and_b32_sdwa v42, v41, v226 dst_sel:DWORD dst_unused:UNUSED_PAD src0_sel:WORD_1 src1_sel:DWORD
	v_and_b32_sdwa v43, v40, v226 dst_sel:DWORD dst_unused:UNUSED_PAD src0_sel:WORD_1 src1_sel:DWORD
	v_add3_u32 v40, v40, v43, s33
	v_add3_u32 v41, v41, v42, s33
	v_and_b32_sdwa v42, v27, v226 dst_sel:DWORD dst_unused:UNUSED_PAD src0_sel:WORD_1 src1_sel:DWORD
	v_and_b32_sdwa v43, v26, v226 dst_sel:DWORD dst_unused:UNUSED_PAD src0_sel:WORD_1 src1_sel:DWORD
	v_add3_u32 v27, v27, v42, s33
	v_add3_u32 v26, v26, v43, s33
	v_and_b32_e32 v27, 0xffff0000, v27
	v_and_b32_e32 v26, 0xffff0000, v26
	v_or_b32_sdwa v27, v27, v41 dst_sel:DWORD dst_unused:UNUSED_PAD src0_sel:DWORD src1_sel:WORD_1
	v_or_b32_sdwa v26, v26, v40 dst_sel:DWORD dst_unused:UNUSED_PAD src0_sel:DWORD src1_sel:WORD_1
	v_mov_b32_e32 v40, v18
	v_mov_b32_e32 v41, v20
	v_mov_b32_e32 v20, v19
	v_pk_fma_f32 v[8:9], v[8:9], v[40:41], v[36:37]
	v_pk_fma_f32 v[18:19], v[30:31], v[20:21], v[34:35]
	v_mov_b32_e32 v20, v10
	v_mov_b32_e32 v21, v12
	v_mov_b32_e32 v30, v22
	v_mov_b32_e32 v31, v24
	v_pk_fma_f32 v[8:9], v[20:21], v[30:31], v[8:9]
	v_mov_b32_e32 v20, v11
	v_mov_b32_e32 v21, v13
	v_mov_b32_e32 v24, v23
	v_pk_fma_f32 v[18:19], v[20:21], v[24:25], v[18:19]
	v_lshlrev_b32_e32 v21, 16, v29
	v_lshlrev_b32_e32 v20, 16, v28
	v_and_b32_e32 v23, 0xffff0000, v29
	v_and_b32_e32 v22, 0xffff0000, v28
	v_pk_mul_f32 v[8:9], v[8:9], v[20:21]
	v_pk_mul_f32 v[18:19], v[18:19], v[22:23]
	v_and_b32_sdwa v20, v9, v226 dst_sel:DWORD dst_unused:UNUSED_PAD src0_sel:WORD_1 src1_sel:DWORD
	v_and_b32_sdwa v21, v8, v226 dst_sel:DWORD dst_unused:UNUSED_PAD src0_sel:WORD_1 src1_sel:DWORD
	v_add3_u32 v8, v8, v21, s33
	v_add3_u32 v9, v9, v20, s33
	v_and_b32_sdwa v20, v19, v226 dst_sel:DWORD dst_unused:UNUSED_PAD src0_sel:WORD_1 src1_sel:DWORD
	v_and_b32_sdwa v21, v18, v226 dst_sel:DWORD dst_unused:UNUSED_PAD src0_sel:WORD_1 src1_sel:DWORD
	v_add3_u32 v19, v19, v20, s33
	v_add3_u32 v18, v18, v21, s33
	v_and_b32_e32 v19, 0xffff0000, v19
	v_and_b32_e32 v18, 0xffff0000, v18
	v_or_b32_sdwa v29, v19, v9 dst_sel:DWORD dst_unused:UNUSED_PAD src0_sel:DWORD src1_sel:WORD_1
	v_or_b32_sdwa v28, v18, v8 dst_sel:DWORD dst_unused:UNUSED_PAD src0_sel:DWORD src1_sel:WORD_1
	global_store_dwordx4 v[38:39], v[26:29], off sc1
	s_load_dwordx2 s[0:1], s[20:21], 0xd0
	s_cbranch_scc1 .LBB0_418
	s_add_i32 s26, s38, -14
	s_waitcnt lgkmcnt(0)
	s_add_u32 s23, s0, s42
	s_addc_u32 s42, s1, s43
	s_lshl_b64 s[18:19], s[26:27], 13
	s_add_u32 s18, s23, s18
	s_addc_u32 s19, s42, s19
	v_lshl_add_u64 v[8:9], v[0:1], 2, s[18:19]
	s_mov_b64 s[18:19], 0x79c4000
	v_lshl_add_u64 v[18:19], v[8:9], 0, s[18:19]
	v_add_co_u32_e32 v8, vcc, 0x79c4000, v8
	s_nop 1
	v_addc_co_u32_e32 v9, vcc, 0, v9, vcc
	global_store_dwordx4 v[8:9], v[14:17], off sc1
	global_store_dwordx4 v[18:19], v[10:13], off offset:16 sc1
; __device__ __forceinline__ void prep_phase(KP P, int l, bool dry) {
;     ...
;       const bool keep = isS || (t >= 3584);
;       if (keep) {
;         float vv[8];
;         unpack8(*(const uint4*)(pr + OV + c0), vv);
;         float* dst = isS ? P->out + O_VS + ((long)(l * 8 + b) * 16 + t) * 2048 + c0
;                          : P->out + O_VP + ((long)(l * 2 + b) * 512 + (t - 3584)) * 2048 + c0;
; #pragma unroll
;         for (int i = 0; i < 8; ++i) dst[i] = vv[i];
;       }
;     }
;     {
;       const int e0 = tid * 8;
;       float x[8];
;       unpack8(*(const uint4*)(pr + OQ + e0), x);
;       float ss = 0.f;
; #pragma unroll
;       for (int i = 0; i < 8; ++i) ss += x[i] * x[i];
;       ss += sx<1>(ss); ss += sx<2>(ss); ss += sx<4>(ss); ss += sx<8>(ss);
;       const float rstd = rsqrtf(ss * (1.f / 128.f) + EPS);
;       const bool isK = e0 >= 2048;
;       const float* g = (isK ? P->k_norm_g : P->q_norm_g) + l * 128 + (e0 & 127);
;       float y[8];
; #pragma unroll
;       for (int i = 0; i < 8; ++i) y[i] = x[i] * rstd * g[i];
;       if (!dry) *(uint4*)(pr + OQ + e0) = pack8(y);
;       if (isK && (isS || t >= 3584)) {
;         float* dst = isS ? P->out + O_KS + ((long)(l * 8 + b) * 16 + t) * 2048 + (e0 - 2048)
;                          : P->out + O_KP + ((long)(l * 2 + b) * 512 + (t - 3584)) * 2048 + (e0 - 2048);
; #pragma unroll
;         for (int i = 0; i < 8; ++i) dst[i] = y[i];
;       }
.LBB0_418:
	s_lshl_b64 s[14:15], s[14:15], 17
	s_waitcnt lgkmcnt(0)
	s_add_u32 s0, s0, s14
	s_addc_u32 s1, s1, s15
	s_lshl_b32 s14, s38, 13
	s_add_u32 s0, s0, s14
	s_addc_u32 s1, s1, 0
	v_lshl_add_u64 v[20:21], v[0:1], 2, s[0:1]
	s_mov_b64 s[0:1], 0x6300000
	v_lshl_add_u64 v[22:23], v[20:21], 0, s[0:1]
	s_movk_i32 s0, 0x7000
	v_add_co_u32_e32 v8, vcc, s0, v32
	s_nop 1
	v_addc_co_u32_e32 v9, vcc, 0, v33, vcc
	global_load_dwordx4 v[8:11], v[8:9], off offset:2048
	s_waitcnt vmcnt(0)
	v_lshlrev_b32_e32 v12, 16, v8
	v_and_b32_e32 v13, 0xffff0000, v8
	v_add_co_u32_e32 v8, vcc, 0x6300000, v20
	v_lshlrev_b32_e32 v14, 16, v9
	v_lshlrev_b32_e32 v18, 16, v11
	v_lshlrev_b32_e32 v16, 16, v10
	v_and_b32_e32 v15, 0xffff0000, v9
	v_and_b32_e32 v19, 0xffff0000, v11
	v_and_b32_e32 v17, 0xffff0000, v10
	v_addc_co_u32_e32 v9, vcc, 0, v21, vcc
	global_store_dwordx4 v[22:23], v[16:19], off offset:16 sc1
	global_store_dwordx4 v[8:9], v[12:15], off sc1
.LBB0_419:
	s_or_b64 exec, exec, s[12:13]
	v_lshl_add_u64 v[8:9], v[0:1], 1, s[10:11]
	v_add_co_u32_e32 v20, vcc, 0x5000, v8
	s_nop 1
	v_addc_co_u32_e32 v21, vcc, 0, v9, vcc
	global_load_dwordx4 v[8:11], v[20:21], off offset:2048
	global_load_dwordx4 v[12:15], v[64:65], off
	global_load_dwordx4 v[16:19], v[64:65], off offset:16
	s_waitcnt vmcnt(2)
	v_lshlrev_b32_e32 v22, 16, v8
	v_and_b32_e32 v23, 0xffff0000, v8
	v_lshlrev_b32_e32 v8, 16, v9
	v_and_b32_e32 v9, 0xffff0000, v9
	v_pk_mul_f32 v[26:27], v[22:23], v[22:23]
	v_pk_mul_f32 v[28:29], v[8:9], v[8:9]
	v_add_f32_e32 v26, v26, v27
	v_lshlrev_b32_e32 v24, 16, v10
	v_and_b32_e32 v25, 0xffff0000, v10
	v_add_f32_e32 v26, v26, v28
	v_pk_mul_f32 v[30:31], v[24:25], v[24:25]
	v_add_f32_e32 v26, v29, v26
	v_lshlrev_b32_e32 v10, 16, v11
	v_and_b32_e32 v11, 0xffff0000, v11
	v_add_f32_e32 v26, v30, v26
	v_pk_mul_f32 v[32:33], v[10:11], v[10:11]
	v_add_f32_e32 v26, v31, v26
	v_add_f32_e32 v26, v32, v26
	v_add_f32_e32 v26, v33, v26
	ds_swizzle_b32 v27, v26 offset:swizzle(SWAP,1)
	s_waitcnt lgkmcnt(0)
	v_add_f32_e32 v26, v26, v27
	ds_swizzle_b32 v27, v26 offset:swizzle(SWAP,2)
	s_waitcnt lgkmcnt(0)
	v_add_f32_e32 v26, v26, v27
	ds_swizzle_b32 v27, v26 offset:swizzle(SWAP,4)
	s_waitcnt lgkmcnt(0)
	v_add_f32_e32 v26, v26, v27
	ds_swizzle_b32 v27, v26 offset:swizzle(SWAP,8)
	s_waitcnt lgkmcnt(0)
	v_add_f32_e32 v26, v26, v27
	v_fmamk_f32 v26, v26, 0x3c000000, v189
	v_mul_f32_e32 v27, 0x4b800000, v26
	v_cmp_gt_f32_e32 vcc, s62, v26
	s_nop 1
	v_cndmask_b32_e32 v26, v26, v27, vcc
	v_rsq_f32_e32 v26, v26
	s_nop 0
	v_mul_f32_e32 v27, 0x45800000, v26
	v_cndmask_b32_e32 v26, v26, v27, vcc
	v_pk_mul_f32 v[22:23], v[26:27], v[22:23] op_sel_hi:[0,1]
	v_pk_mul_f32 v[8:9], v[26:27], v[8:9] op_sel_hi:[0,1]
	v_pk_mul_f32 v[24:25], v[26:27], v[24:25] op_sel_hi:[0,1]
	v_pk_mul_f32 v[10:11], v[26:27], v[10:11] op_sel_hi:[0,1]
	s_waitcnt vmcnt(1)
	v_pk_mul_f32 v[12:13], v[12:13], v[22:23]
	v_pk_mul_f32 v[14:15], v[14:15], v[8:9]
	s_waitcnt vmcnt(0)
	v_pk_mul_f32 v[8:9], v[16:17], v[24:25]
	v_pk_mul_f32 v[10:11], v[18:19], v[10:11]
	v_and_b32_sdwa v17, v12, v226 dst_sel:DWORD dst_unused:UNUSED_PAD src0_sel:WORD_1 src1_sel:DWORD
	v_and_b32_sdwa v18, v15, v226 dst_sel:DWORD dst_unused:UNUSED_PAD src0_sel:WORD_1 src1_sel:DWORD
	v_and_b32_sdwa v19, v13, v226 dst_sel:DWORD dst_unused:UNUSED_PAD src0_sel:WORD_1 src1_sel:DWORD
	v_and_b32_sdwa v22, v10, v226 dst_sel:DWORD dst_unused:UNUSED_PAD src0_sel:WORD_1 src1_sel:DWORD
	v_and_b32_sdwa v24, v11, v226 dst_sel:DWORD dst_unused:UNUSED_PAD src0_sel:WORD_1 src1_sel:DWORD
	v_and_b32_sdwa v25, v9, v226 dst_sel:DWORD dst_unused:UNUSED_PAD src0_sel:WORD_1 src1_sel:DWORD
	v_and_b32_sdwa v16, v14, v226 dst_sel:DWORD dst_unused:UNUSED_PAD src0_sel:WORD_1 src1_sel:DWORD
	v_and_b32_sdwa v23, v8, v226 dst_sel:DWORD dst_unused:UNUSED_PAD src0_sel:WORD_1 src1_sel:DWORD
	v_add3_u32 v26, v12, v17, s33
	v_add3_u32 v17, v15, v18, s33
	v_add3_u32 v18, v13, v19, s33
	v_add3_u32 v19, v10, v22, s33
	v_add3_u32 v22, v11, v24, s33
	v_add3_u32 v24, v9, v25, s33
	v_add3_u32 v16, v14, v16, s33
	v_add3_u32 v23, v8, v23, s33
	v_and_b32_e32 v17, 0xffff0000, v17
	v_and_b32_e32 v18, 0xffff0000, v18
	v_and_b32_e32 v22, 0xffff0000, v22
	v_and_b32_e32 v24, 0xffff0000, v24
	v_or_b32_sdwa v17, v17, v16 dst_sel:DWORD dst_unused:UNUSED_PAD src0_sel:DWORD src1_sel:WORD_1
	v_or_b32_sdwa v16, v18, v26 dst_sel:DWORD dst_unused:UNUSED_PAD src0_sel:DWORD src1_sel:WORD_1
	v_or_b32_sdwa v19, v22, v19 dst_sel:DWORD dst_unused:UNUSED_PAD src0_sel:DWORD src1_sel:WORD_1
	v_or_b32_sdwa v18, v24, v23 dst_sel:DWORD dst_unused:UNUSED_PAD src0_sel:DWORD src1_sel:WORD_1
	global_store_dwordx4 v[20:21], v[16:19], off offset:2048 sc1
	s_and_saveexec_b64 s[0:1], s[4:5]
	s_cbranch_execz .LBB0_383
	s_load_dwordx2 s[10:11], s[20:21], 0xd0
	s_add_i32 s12, s39, s60
	s_ashr_i32 s13, s12, 31
	s_lshl_b64 s[12:13], s[12:13], 17
	s_waitcnt lgkmcnt(0)
	s_add_u32 s10, s10, s12
	s_addc_u32 s11, s11, s13
	s_lshl_b32 s12, s38, 13
	s_add_u32 s10, s10, s12
	s_addc_u32 s11, s11, 0
	v_lshl_add_u64 v[16:17], v[66:67], 2, s[10:11]
	v_add_co_u32_e32 v16, vcc, 0x60fe000, v16
	s_nop 1
	v_addc_co_u32_e32 v17, vcc, 0, v17, vcc
	global_store_dwordx4 v[16:17], v[12:15], off sc1
	global_store_dwordx4 v[16:17], v[8:11], off offset:16 sc1
	s_branch .LBB0_383
